# S5 group-to-XCD remap (4 groups sharing a z line on one XCD) + flat_store->global_store in GEMM epilogues
# speedup vs baseline: 1.0508x; 1.0021x over previous
; #define BAR __builtin_amdgcn_s_barrier()
; #define ZERO_ACC() do { _Pragma("unroll") for (int a = 0; a < 2; ++a) _Pragma("unroll") for (int b = 0; b < 2; ++b) _Pragma("unroll") for (int m = 0; m < 4; ++m) _Pragma("unroll") for (int n = 0; n < 2; ++n) acc[a][b][m][n] = (f32x4){0.f, 0.f, 0.f, 0.f}; } while (0)
; #define EPI_ROWS(...) _Pragma("unroll") for (int ai = 0; ai < 2; ++ai) _Pragma("unroll") for (int m = 0; m < 4; ++m) { const int rr = ai * 128 + wr * 64 + m * 16 + fr; __VA_ARGS__ }
; template <class Units>
; DI void gemm_phase(LAS unsigned char* lds, const int wid, const int lda, const int ldb, const int K, const Units& U) {
;     ...
;         if (wr == 0) BAR;
;         Ecur(acc, wr, wc, fr, fq);
;         if (!has_next) break;
;         ZERO_ACC();
;         cA = nA; cB = nB; Ecur = Enxt;
;         if (wr == 1) BAR;
;     DI void operator()(const Acc& acc, int wr, int wc, int fr, int fq) const {
;         EPI_ROWS(const size_t row = (size_t)g * 2048 + row0 + rr;
;             _Pragma("unroll") for (int n = 0; n < 2; ++n) { const int cc = wc * 32 + 8 * fq + 4 * n; *(f32x4*)(S + row * 128 + cc) = acc[ai][0][m][n]; })
;     }
.LBB0_347:
	s_ashr_i32 s9, s8, 31
	s_ashr_i32 s7, s6, 31
	s_lshl_b64 s[8:9], s[8:9], 20
	v_lshl_add_u64 v[88:89], s[6:7], 0, v[66:67]
	s_add_u32 s8, s34, s8
	v_lshlrev_b64 v[88:89], 9, v[88:89]
	s_addc_u32 s9, s35, s9
	v_lshl_add_u64 v[88:89], s[8:9], 0, v[88:89]
	v_lshl_add_u64 v[88:89], v[88:89], 0, v[82:83]
	global_store_dwordx4 v[88:89], v[24:27], off
	global_store_dwordx4 v[88:89], v[28:31], off offset:16
	s_andn2_b64 vcc, exec, s[18:19]
	v_lshl_add_u64 v[24:25], s[6:7], 0, v[68:69]
	v_lshlrev_b64 v[24:25], 9, v[24:25]
	v_lshl_add_u64 v[24:25], s[8:9], 0, v[24:25]
	v_lshl_add_u64 v[24:25], v[24:25], 0, v[82:83]
	global_store_dwordx4 v[24:25], v[16:19], off
	global_store_dwordx4 v[24:25], v[20:23], off offset:16
	s_nop 0
	v_lshl_add_u64 v[16:17], s[6:7], 0, v[70:71]
	v_lshlrev_b64 v[16:17], 9, v[16:17]
	v_lshl_add_u64 v[16:17], s[8:9], 0, v[16:17]
	v_lshl_add_u64 v[16:17], v[16:17], 0, v[82:83]
	global_store_dwordx4 v[16:17], v[8:11], off
	global_store_dwordx4 v[16:17], v[12:15], off offset:16
	s_nop 0
	v_lshl_add_u64 v[8:9], s[6:7], 0, v[72:73]
	v_lshlrev_b64 v[8:9], 9, v[8:9]
	v_lshl_add_u64 v[8:9], s[8:9], 0, v[8:9]
	v_lshl_add_u64 v[8:9], v[8:9], 0, v[82:83]
	global_store_dwordx4 v[8:9], v[0:3], off
	global_store_dwordx4 v[8:9], v[4:7], off offset:16
	s_nop 0
	v_lshl_add_u64 v[0:1], s[6:7], 0, v[74:75]
	v_lshlrev_b64 v[0:1], 9, v[0:1]
	v_lshl_add_u64 v[0:1], s[8:9], 0, v[0:1]
	v_lshl_add_u64 v[0:1], v[0:1], 0, v[82:83]
	global_store_dwordx4 v[0:1], v[56:59], off
	global_store_dwordx4 v[0:1], v[60:63], off offset:16
	v_lshl_add_u64 v[0:1], s[6:7], 0, v[76:77]
	v_lshlrev_b64 v[0:1], 9, v[0:1]
	v_lshl_add_u64 v[0:1], s[8:9], 0, v[0:1]
	v_lshl_add_u64 v[0:1], v[0:1], 0, v[82:83]
	global_store_dwordx4 v[0:1], v[48:51], off
	global_store_dwordx4 v[0:1], v[52:55], off offset:16
	v_lshl_add_u64 v[0:1], s[6:7], 0, v[78:79]
	v_lshlrev_b64 v[0:1], 9, v[0:1]
	v_lshl_add_u64 v[0:1], s[8:9], 0, v[0:1]
	v_lshl_add_u64 v[0:1], v[0:1], 0, v[82:83]
	global_store_dwordx4 v[0:1], v[40:43], off
	global_store_dwordx4 v[0:1], v[44:47], off offset:16
	v_lshl_add_u64 v[0:1], s[6:7], 0, v[80:81]
	v_lshlrev_b64 v[0:1], 9, v[0:1]
	v_lshl_add_u64 v[0:1], s[8:9], 0, v[0:1]
	v_lshl_add_u64 v[0:1], v[0:1], 0, v[82:83]
	s_mov_b64 s[6:7], -1
	global_store_dwordx4 v[0:1], v[32:35], off
	global_store_dwordx4 v[0:1], v[36:39], off offset:16
	s_cbranch_vccnz .LBB0_342
	s_andn2_b64 vcc, exec, s[0:1]
	s_cbranch_vccnz .LBB0_341
	s_barrier
	s_branch .LBB0_341

; #define LAS __attribute__((address_space(3)))
; __global__ void __launch_bounds__(512, 2) mega(Params p) {
;     ...
;     {
;         { const bool act = bx < 128; const int b = (bx >> 5) & 3, g = bx & 31;
;           LAS float* ex = (LAS float*)lds;
;           float c_r = 1.f, c_i = 0.f, hr = 0.f, hi = 0.f;
;           const float* Sp = Sbuf + ((size_t)g * 2048 + b * 512 + wave * 64) * 128 + lane; bf16_t* Hp = Ap + ((size_t)g * 2048 + b * 512 + wave * 64) * 384 + lane;
;           if (act) {
;             const float dt = __expf(p.in[12][g]); const float zr = p.in[10][g * 64 + lane] * dt * 16.f, zi = p.in[11][g * 64 + lane] * dt * 16.f;
;             float sn, cs; sincos_acc(zi, sn, cs); const float mag = __expf(zr); c_r = mag * cs; c_i = mag * sn;
.LBB0_663:
	s_cmp_lt_i32 s74, 4
	s_cselect_b64 s[0:1], -1, 0
	s_cmp_gt_i32 s75, 3
	s_cselect_b64 s[2:3], -1, 0
	s_and_b64 s[0:1], s[0:1], s[2:3]
	s_andn2_b64 vcc, exec, s[0:1]
	s_cbranch_vccnz .LBB0_801
	v_readlane_b32 s6, v254, 0
	v_readlane_b32 s7, v254, 1
	s_waitcnt lgkmcnt(0)
	s_load_dwordx8 s[12:19], s[6:7], 0x48
	s_load_dwordx2 s[0:1], s[6:7], 0xd0
	s_load_dwordx2 s[20:21], s[6:7], 0x88
	s_cmpk_lt_i32 s84, 0x80
	s_cselect_b64 s[4:5], -1, 0
	s_cmpk_gt_i32 s84, 0x7f
	s_cselect_b64 s[30:31], -1, 0
	s_and_b32 s10, s84, 7
	s_lshl_b32 s10, s10, 2
	s_bfe_u32 s2, s84, 0x20003
	s_or_b32 s10, s10, s2
	s_lshl_b32 s2, s84, 4
	s_lshl_b32 s11, s10, 11
	s_and_b32 s51, s2, 0x600
	s_ashr_i32 s3, s77, 31
	s_add_i32 s58, s84, 0xffffff80
	v_mbcnt_lo_u32_b32 v128, -1, 0
	v_mbcnt_hi_u32_b32 v128, -1, v128
	s_and_b64 vcc, exec, s[30:31]
	v_ashrrev_i32_e32 v129, 31, v128
	s_cbranch_vccnz .LBB0_672
	s_lshl_b32 s6, s10, 2
	v_mov_b32_e32 v0, s6
	s_waitcnt lgkmcnt(0)
	global_load_dword v4, v0, s[18:19]
	v_lshl_add_u32 v0, s10, 6, v128
	v_ashrrev_i32_e32 v1, 31, v0
	v_lshlrev_b64 v[0:1], 2, v[0:1]
	v_lshl_add_u64 v[2:3], s[16:17], 0, v[0:1]
	global_load_dword v5, v[2:3], off
	v_lshl_add_u64 v[0:1], s[14:15], 0, v[0:1]
	global_load_dword v2, v[0:1], off
	s_waitcnt vmcnt(0)
	v_mul_f32_e32 v0, 0x3fb8aa3b, v4
	v_exp_f32_e32 v3, v0
	s_nop 0
	v_mul_f32_e32 v0, v3, v5
	v_mul_f32_e32 v4, 0x41800000, v0
	v_cmp_nlt_f32_e64 s[6:7], |v4|, 0.5
	s_and_saveexec_b64 s[8:9], s[6:7]
	s_xor_b64 s[6:7], exec, s[8:9]
	s_cbranch_execz .LBB0_667
	v_mul_f32_e32 v0, 0.15915494, v4
	v_floor_f32_e32 v0, v0
	v_fma_f32 v0, v4, 0.15915494, -v0
	v_sin_f32_e32 v1, v0
	v_cos_f32_e32 v0, v0

; __global__ void __launch_bounds__(512, 2) mega(Params p) {
;     ...
;             for (int c0 = 0; c0 < 64; c0 += 16) { float sr[16], si[16];
; #pragma unroll
;                 for (int k = 0; k < 16; ++k) { sr[k] = Sp[(size_t)(c0 + k) * 128]; si[k] = Sp[(size_t)(c0 + k) * 128 + 64]; }
; #pragma unroll
;                 for (int k = 0; k < 16; ++k) { const unsigned w = pk2(hr, hi); Hp[(size_t)(c0 + k) * 384] = (bf16_t)(w & 0xffffu); Hp[(size_t)(c0 + k) * 384 + 64] = (bf16_t)(w >> 16);
;                     const float n_r = c_r * hr - c_i * hi + sr[k], n_i = c_r * hi + c_i * hr + si[k]; hr = n_r; hi = n_i; } }
.LBB0_683:
	v_lshl_add_u64 v[14:15], s[90:91], 0, v[8:9]
	v_add_co_u32_e64 v22, s[6:7], s14, v14
	v_lshl_add_u64 v[16:17], s[90:91], 0, v[10:11]
	s_nop 0
	v_addc_co_u32_e64 v23, s[6:7], 0, v15, s[6:7]
	v_add_co_u32_e64 v24, s[6:7], s15, v16
	v_cvt_pk_bf16_f32 v38, v12, s0
	v_pk_mul_f32 v[18:19], v[0:1], v[12:13]
	v_add_co_u32_e32 v20, vcc, 0x17800000, v14
	v_addc_co_u32_e64 v25, s[6:7], 0, v17, s[6:7]
	v_cvt_pk_bf16_f32 v39, v13, s0
	v_sub_f32_e32 v50, v18, v19
	v_addc_co_u32_e32 v21, vcc, 0, v15, vcc
	global_load_dword v14, v[22:23], off
	global_load_dword v15, v[22:23], off offset:256
	global_load_dword v18, v[22:23], off offset:512
	global_load_dword v19, v[22:23], off offset:768
	global_load_dword v26, v[22:23], off offset:1024
	global_load_dword v27, v[22:23], off offset:1280
	global_load_dword v28, v[22:23], off offset:1536
	global_load_dword v29, v[22:23], off offset:1792
	global_load_dword v30, v[22:23], off offset:2048
	global_load_dword v31, v[22:23], off offset:2304
	global_load_dword v32, v[22:23], off offset:2560
	global_load_dword v33, v[22:23], off offset:2816
	global_load_dword v34, v[22:23], off offset:3072
	global_load_dword v35, v[22:23], off offset:3328
	global_load_dword v36, v[22:23], off offset:3584
	global_load_dword v37, v[22:23], off offset:3840
	s_nop 0
	global_store_short v[24:25], v38, off
	global_store_short v[24:25], v39, off offset:128
	global_load_dword v52, v[20:21], off
	global_load_dword v53, v[20:21], off offset:256
	global_load_dword v23, v[20:21], off offset:512
	global_load_dword v22, v[20:21], off offset:768
	s_nop 0
	global_load_dword v39, v[20:21], off offset:1024
	global_load_dword v38, v[20:21], off offset:1280
	global_load_dword v41, v[20:21], off offset:1536
	global_load_dword v40, v[20:21], off offset:1792
	global_load_dword v43, v[20:21], off offset:2048
	global_load_dword v42, v[20:21], off offset:2304
	global_load_dword v44, v[20:21], off offset:2560
	global_load_dword v45, v[20:21], off offset:2816
	global_load_dword v46, v[20:21], off offset:3072
	global_load_dword v47, v[20:21], off offset:3328
	global_load_dword v48, v[20:21], off offset:3584
	global_load_dword v49, v[20:21], off offset:3840
	v_pk_mul_f32 v[12:13], v[0:1], v[12:13] op_sel:[0,1] op_sel_hi:[1,0]
	s_add_i32 s3, s3, 16
	v_add_f32_e32 v51, v12, v13
	v_add_co_u32_e64 v12, s[6:7], s16, v16
	v_lshl_add_u64 v[8:9], v[8:9], 0, s[4:5]
	s_nop 0
	v_addc_co_u32_e64 v13, s[6:7], 0, v17, s[6:7]
	v_add_co_u32_e64 v16, s[6:7], s17, v16
	v_lshl_add_u64 v[10:11], v[10:11], 0, s[8:9]
	s_nop 0
	v_addc_co_u32_e64 v17, s[6:7], 0, v17, s[6:7]
	s_cmp_gt_u32 s3, 47
	s_waitcnt vmcnt(15)
	v_add_f32_e32 v20, v50, v52
	s_waitcnt vmcnt(14)
	v_add_f32_e32 v50, v51, v53
	v_cvt_pk_bf16_f32 v21, v20, s0
	v_cvt_pk_bf16_f32 v52, v50, s0
	v_pk_mul_f32 v[50:51], v[0:1], v[50:51] op_sel_hi:[1,0]
	global_store_short v[24:25], v21, off offset:768
	global_store_short v[24:25], v52, off offset:896
	v_pk_fma_f32 v[52:53], v[2:3], v[20:21], v[50:51]
	v_pk_fma_f32 v[20:21], v[2:3], v[20:21], v[50:51] op_sel_hi:[1,0,1] neg_lo:[0,0,1] neg_hi:[0,0,1]
	s_nop 0
	v_mov_b32_e32 v53, v21
	s_waitcnt vmcnt(14)
	v_pk_add_f32 v[20:21], v[52:53], v[22:23]
	s_nop 0
	v_cvt_pk_bf16_f32 v50, v21, s0
	v_cvt_pk_bf16_f32 v51, v20, s0
	v_pk_mul_f32 v[22:23], v[6:7], v[20:21]
	global_store_short v[24:25], v50, off offset:1536
	global_store_short v[24:25], v51, off offset:1664
	v_pk_fma_f32 v[50:51], v[4:5], v[20:21], v[22:23] op_sel:[0,0,1] op_sel_hi:[1,1,0]
	v_pk_fma_f32 v[20:21], v[4:5], v[20:21], v[22:23] op_sel:[0,0,1] op_sel_hi:[1,1,0] neg_lo:[0,0,1] neg_hi:[0,0,1]
	s_nop 0
	v_mov_b32_e32 v51, v21
	s_waitcnt vmcnt(14)
	v_pk_add_f32 v[20:21], v[50:51], v[38:39]
	s_nop 0
	v_cvt_pk_bf16_f32 v38, v21, s0
	v_cvt_pk_bf16_f32 v39, v20, s0
	v_pk_mul_f32 v[22:23], v[6:7], v[20:21]
	global_store_short v[24:25], v38, off offset:2304
	global_store_short v[24:25], v39, off offset:2432
	v_pk_fma_f32 v[38:39], v[4:5], v[20:21], v[22:23] op_sel:[0,0,1] op_sel_hi:[1,1,0]
	v_pk_fma_f32 v[20:21], v[4:5], v[20:21], v[22:23] op_sel:[0,0,1] op_sel_hi:[1,1,0] neg_lo:[0,0,1] neg_hi:[0,0,1]
	s_nop 0
	v_mov_b32_e32 v39, v21
	s_waitcnt vmcnt(14)
	v_pk_add_f32 v[20:21], v[38:39], v[40:41]
	s_nop 0
	v_cvt_pk_bf16_f32 v38, v21, s0
	v_cvt_pk_bf16_f32 v39, v20, s0
	v_pk_mul_f32 v[22:23], v[6:7], v[20:21]
	global_store_short v[24:25], v38, off offset:3072
	global_store_short v[24:25], v39, off offset:3200
	v_pk_fma_f32 v[38:39], v[4:5], v[20:21], v[22:23] op_sel:[0,0,1] op_sel_hi:[1,1,0]
	v_pk_fma_f32 v[20:21], v[4:5], v[20:21], v[22:23] op_sel:[0,0,1] op_sel_hi:[1,1,0] neg_lo:[0,0,1] neg_hi:[0,0,1]
	s_nop 0
	v_mov_b32_e32 v39, v21
	s_waitcnt vmcnt(14)
	v_pk_add_f32 v[20:21], v[38:39], v[42:43]
	s_nop 0
	v_cvt_pk_bf16_f32 v23, v21, s0
	v_cvt_pk_bf16_f32 v39, v20, s0
	v_mul_f32_e32 v22, v1, v20
	v_mul_f32_e32 v38, v0, v20
	global_store_short v[24:25], v23, off offset:3840
	global_store_short v[24:25], v39, off offset:3968
	v_pk_fma_f32 v[22:23], v[0:1], v[20:21], v[22:23] op_sel:[0,1,0] op_sel_hi:[1,0,0] neg_lo:[0,0,1] neg_hi:[0,0,1]
	v_pk_fma_f32 v[20:21], v[0:1], v[20:21], v[38:39] op_sel_hi:[1,1,0]
	s_nop 0
	v_mov_b32_e32 v23, v21
	s_waitcnt vmcnt(14)
; __global__ void __launch_bounds__(512, 2) mega(Params p) {
;     ...
;             for (int c0 = 0; c0 < 64; c0 += 16) { float sr[16], si[16];
; #pragma unroll
;                 for (int k = 0; k < 16; ++k) { sr[k] = Sp[(size_t)(c0 + k) * 128]; si[k] = Sp[(size_t)(c0 + k) * 128 + 64]; }
; #pragma unroll
;                 for (int k = 0; k < 16; ++k) { const unsigned w = pk2(hr, hi); Hp[(size_t)(c0 + k) * 384] = (bf16_t)(w & 0xffffu); Hp[(size_t)(c0 + k) * 384 + 64] = (bf16_t)(w >> 16);
;                     const float n_r = c_r * hr - c_i * hi + sr[k], n_i = c_r * hi + c_i * hr + si[k]; hr = n_r; hi = n_i; } }
;             if (wave == 7) { float* o = p.out + O_S5P + (((size_t)b * 32 + g) * 64 + lane) * 2; o[0] = hr; o[1] = hi; }
	v_pk_add_f32 v[20:21], v[22:23], v[44:45]
	s_nop 0
	v_cvt_pk_bf16_f32 v24, v20, s0
	v_cvt_pk_bf16_f32 v25, v21, s0
	v_pk_mul_f32 v[22:23], v[6:7], v[20:21]
	global_store_short v[12:13], v24, off offset:512
	global_store_short v[12:13], v25, off offset:640
	v_pk_fma_f32 v[24:25], v[4:5], v[20:21], v[22:23] op_sel:[0,0,1] op_sel_hi:[1,1,0] neg_lo:[0,0,1] neg_hi:[0,0,1]
	v_pk_fma_f32 v[20:21], v[4:5], v[20:21], v[22:23] op_sel:[0,0,1] op_sel_hi:[1,1,0]
	s_nop 0
	v_mov_b32_e32 v25, v21
	s_waitcnt vmcnt(14)
	v_pk_add_f32 v[20:21], v[24:25], v[46:47]
	s_nop 0
	v_cvt_pk_bf16_f32 v24, v20, s0
	v_cvt_pk_bf16_f32 v25, v21, s0
	v_pk_mul_f32 v[22:23], v[6:7], v[20:21]
	global_store_short v[12:13], v24, off offset:1280
	global_store_short v[12:13], v25, off offset:1408
	v_pk_fma_f32 v[24:25], v[4:5], v[20:21], v[22:23] op_sel:[0,0,1] op_sel_hi:[1,1,0] neg_lo:[0,0,1] neg_hi:[0,0,1]
	v_pk_fma_f32 v[20:21], v[4:5], v[20:21], v[22:23] op_sel:[0,0,1] op_sel_hi:[1,1,0]
	s_nop 0
	v_mov_b32_e32 v25, v21
	s_waitcnt vmcnt(14)
	v_pk_add_f32 v[20:21], v[24:25], v[48:49]
	s_nop 0
	v_cvt_pk_bf16_f32 v24, v20, s0
	v_cvt_pk_bf16_f32 v25, v21, s0
	v_pk_mul_f32 v[22:23], v[6:7], v[20:21]
	global_store_short v[12:13], v24, off offset:2048
	global_store_short v[12:13], v25, off offset:2176
	v_pk_fma_f32 v[24:25], v[4:5], v[20:21], v[22:23] op_sel:[0,0,1] op_sel_hi:[1,1,0] neg_lo:[0,0,1] neg_hi:[0,0,1]
	v_pk_fma_f32 v[20:21], v[4:5], v[20:21], v[22:23] op_sel:[0,0,1] op_sel_hi:[1,1,0]
	s_nop 0
	v_mov_b32_e32 v25, v21
	v_pk_add_f32 v[14:15], v[24:25], v[14:15]
	s_nop 0
	v_cvt_pk_bf16_f32 v22, v14, s0
	v_cvt_pk_bf16_f32 v23, v15, s0
	v_pk_mul_f32 v[20:21], v[6:7], v[14:15]
	global_store_short v[12:13], v22, off offset:2816
	global_store_short v[12:13], v23, off offset:2944
	v_pk_fma_f32 v[22:23], v[4:5], v[14:15], v[20:21] op_sel:[0,0,1] op_sel_hi:[1,1,0] neg_lo:[0,0,1] neg_hi:[0,0,1]
	v_pk_fma_f32 v[14:15], v[4:5], v[14:15], v[20:21] op_sel:[0,0,1] op_sel_hi:[1,1,0]
	s_nop 0
	v_mov_b32_e32 v23, v15
	v_pk_add_f32 v[14:15], v[22:23], v[18:19]
	s_nop 0
	v_cvt_pk_bf16_f32 v20, v14, s0
	v_pk_mul_f32 v[18:19], v[6:7], v[14:15]
	v_cvt_pk_bf16_f32 v21, v15, s0
	global_store_short v[12:13], v20, off offset:3584
	global_store_short v[12:13], v21, off offset:3712
	v_pk_fma_f32 v[12:13], v[4:5], v[14:15], v[18:19] op_sel:[0,0,1] op_sel_hi:[1,1,0] neg_lo:[0,0,1] neg_hi:[0,0,1]
	v_pk_fma_f32 v[14:15], v[4:5], v[14:15], v[18:19] op_sel:[0,0,1] op_sel_hi:[1,1,0]
	s_nop 0
	v_mov_b32_e32 v13, v15
	v_pk_add_f32 v[12:13], v[12:13], v[26:27]
	s_nop 0
	v_cvt_pk_bf16_f32 v18, v12, s0
	v_cvt_pk_bf16_f32 v19, v13, s0
	v_pk_mul_f32 v[14:15], v[6:7], v[12:13]
	global_store_short v[16:17], v18, off offset:256
	global_store_short v[16:17], v19, off offset:384
	v_pk_fma_f32 v[18:19], v[4:5], v[12:13], v[14:15] op_sel:[0,0,1] op_sel_hi:[1,1,0] neg_lo:[0,0,1] neg_hi:[0,0,1]
	v_pk_fma_f32 v[12:13], v[4:5], v[12:13], v[14:15] op_sel:[0,0,1] op_sel_hi:[1,1,0]
	s_nop 0
	v_mov_b32_e32 v19, v13
	v_pk_add_f32 v[12:13], v[18:19], v[28:29]
	s_nop 0
	v_cvt_pk_bf16_f32 v18, v12, s0
	v_cvt_pk_bf16_f32 v19, v13, s0
	v_pk_mul_f32 v[14:15], v[6:7], v[12:13]
	global_store_short v[16:17], v18, off offset:1024
	global_store_short v[16:17], v19, off offset:1152
	v_pk_fma_f32 v[18:19], v[4:5], v[12:13], v[14:15] op_sel:[0,0,1] op_sel_hi:[1,1,0] neg_lo:[0,0,1] neg_hi:[0,0,1]
	v_pk_fma_f32 v[12:13], v[4:5], v[12:13], v[14:15] op_sel:[0,0,1] op_sel_hi:[1,1,0]
	s_nop 0
	v_mov_b32_e32 v19, v13
	v_pk_add_f32 v[12:13], v[18:19], v[30:31]
	s_nop 0
	v_cvt_pk_bf16_f32 v18, v12, s0
	v_cvt_pk_bf16_f32 v19, v13, s0
	v_pk_mul_f32 v[14:15], v[6:7], v[12:13]
	global_store_short v[16:17], v18, off offset:1792
	global_store_short v[16:17], v19, off offset:1920
	v_pk_fma_f32 v[18:19], v[4:5], v[12:13], v[14:15] op_sel:[0,0,1] op_sel_hi:[1,1,0] neg_lo:[0,0,1] neg_hi:[0,0,1]
	v_pk_fma_f32 v[12:13], v[4:5], v[12:13], v[14:15] op_sel:[0,0,1] op_sel_hi:[1,1,0]
	s_nop 0
	v_mov_b32_e32 v19, v13
	v_pk_add_f32 v[12:13], v[18:19], v[32:33]
	s_nop 0
	v_cvt_pk_bf16_f32 v18, v12, s0
	v_cvt_pk_bf16_f32 v19, v13, s0
	v_pk_mul_f32 v[14:15], v[6:7], v[12:13]
	global_store_short v[16:17], v18, off offset:2560
	global_store_short v[16:17], v19, off offset:2688
	v_pk_fma_f32 v[18:19], v[4:5], v[12:13], v[14:15] op_sel:[0,0,1] op_sel_hi:[1,1,0] neg_lo:[0,0,1] neg_hi:[0,0,1]
	v_pk_fma_f32 v[12:13], v[4:5], v[12:13], v[14:15] op_sel:[0,0,1] op_sel_hi:[1,1,0]
	s_nop 0
	v_mov_b32_e32 v19, v13
	v_pk_add_f32 v[12:13], v[18:19], v[34:35]
	s_nop 0
	v_cvt_pk_bf16_f32 v18, v12, s0
	v_pk_mul_f32 v[14:15], v[6:7], v[12:13]
	v_cvt_pk_bf16_f32 v19, v13, s0
	global_store_short v[16:17], v18, off offset:3328
	global_store_short v[16:17], v19, off offset:3456
	v_pk_fma_f32 v[16:17], v[4:5], v[12:13], v[14:15] op_sel:[0,0,1] op_sel_hi:[1,1,0] neg_lo:[0,0,1] neg_hi:[0,0,1]
	v_pk_fma_f32 v[12:13], v[4:5], v[12:13], v[14:15] op_sel:[0,0,1] op_sel_hi:[1,1,0]
	s_nop 0
	v_mov_b32_e32 v17, v13
	v_pk_add_f32 v[12:13], v[16:17], v[36:37]
	s_cbranch_scc0 .LBB0_683
	s_cmp_eq_u32 s87, 7
	s_cbranch_scc0 .LBB0_686
	s_and_b32 s3, s84, 0x60
	s_or_b32 s3, s3, s10
	s_lshl_b32 s4, s3, 6
	s_mov_b32 s5, 0
	v_lshl_add_u64 v[0:1], v[128:129], 0, s[4:5]
	v_lshl_add_u64 v[0:1], v[0:1], 3, s[0:1]
	v_add_co_u32_e32 v0, vcc, 0x809e000, v0
	s_nop 1
	v_addc_co_u32_e32 v1, vcc, 0, v1, vcc
	global_store_dwordx2 v[0:1], v[12:13], off

; #define BAR __builtin_amdgcn_s_barrier()
; #define ZERO_ACC() do { _Pragma("unroll") for (int a = 0; a < 2; ++a) _Pragma("unroll") for (int b = 0; b < 2; ++b) _Pragma("unroll") for (int m = 0; m < 4; ++m) _Pragma("unroll") for (int n = 0; n < 2; ++n) acc[a][b][m][n] = (f32x4){0.f, 0.f, 0.f, 0.f}; } while (0)
; #define EPI_ROWS(...) _Pragma("unroll") for (int ai = 0; ai < 2; ++ai) _Pragma("unroll") for (int m = 0; m < 4; ++m) { const int rr = ai * 128 + wr * 64 + m * 16 + fr; __VA_ARGS__ }
; template <class Units>
; DI void gemm_phase(LAS unsigned char* lds, const int wid, const int lda, const int ldb, const int K, const Units& U) {
;     ...
;         if (wr == 0) BAR;
;         Ecur(acc, wr, wc, fr, fq);
;         if (!has_next) break;
;         ZERO_ACC();
;         cA = nA; cB = nB; Ecur = Enxt;
;         if (wr == 1) BAR;
;     DI void operator()(const Acc& acc, int wr, int wc, int fr, int fq) const {
;         EPI_ROWS(const size_t row = row0 + rr;
;             _Pragma("unroll") for (int bj = 0; bj < 2; ++bj) { const int cc = bj * 128 + wc * 32 + 8 * fq; const f32x4 v0 = acc[ai][bj][m][0], v1 = acc[ai][bj][m][1];
;                 u32x4 w; w.x = pk2(v0[0], v0[1]); w.y = pk2(v0[2], v0[3]); w.z = pk2(v1[0], v1[1]); w.w = pk2(v1[2], v1[3]); *(u32x4*)(y + row * 1024 + col0 + cc) = w; })
;     }
.LBB0_936:
	v_add_u32_e32 v150, s36, v137
	v_cvt_pk_bf16_f32 v68, v68, v69
	v_cvt_pk_bf16_f32 v69, v70, v71
	v_cvt_pk_bf16_f32 v70, v64, v65
	v_add_u32_e32 v64, s36, v142
	v_ashrrev_i32_e32 v151, 31, v150
	v_ashrrev_i32_e32 v65, 31, v64
	v_lshlrev_b64 v[150:151], 11, v[150:151]
	s_ashr_i32 s23, s22, 31
	v_lshlrev_b64 v[64:65], 11, v[64:65]
	v_cvt_pk_bf16_f32 v124, v124, v125
	v_cvt_pk_bf16_f32 v125, v126, v127
	v_cvt_pk_bf16_f32 v126, v120, v121
	v_lshl_add_u64 v[120:121], s[4:5], 0, v[150:151]
	s_lshl_b64 s[14:15], s[22:23], 1
	v_cvt_pk_bf16_f32 v60, v60, v61
	v_cvt_pk_bf16_f32 v61, v62, v63
	v_cvt_pk_bf16_f32 v62, v56, v57
	v_lshl_add_u64 v[56:57], s[4:5], 0, v[64:65]
	v_lshl_add_u64 v[120:121], v[120:121], 0, s[14:15]
	v_cvt_pk_bf16_f32 v108, v108, v109
	v_cvt_pk_bf16_f32 v109, v110, v111
	v_cvt_pk_bf16_f32 v110, v104, v105
	v_add_u32_e32 v104, s36, v139
	v_lshl_add_u64 v[56:57], v[56:57], 0, s[14:15]
	v_cvt_pk_bf16_f32 v44, v44, v45
	v_cvt_pk_bf16_f32 v45, v46, v47
	v_cvt_pk_bf16_f32 v46, v40, v41
	v_add_u32_e32 v40, s36, v143
	v_lshl_add_u64 v[120:121], v[120:121], 0, v[132:133]
	v_cvt_pk_bf16_f32 v111, v106, v107
	v_ashrrev_i32_e32 v105, 31, v104
	v_lshl_add_u64 v[56:57], v[56:57], 0, v[132:133]
	v_cvt_pk_bf16_f32 v47, v42, v43
	v_ashrrev_i32_e32 v41, 31, v40
	global_store_dwordx4 v[120:121], v[108:111], off offset:256
	global_store_dwordx4 v[56:57], v[44:47], off offset:256
	v_cvt_pk_bf16_f32 v92, v92, v93
	v_lshlrev_b64 v[108:109], 11, v[104:105]
	v_lshlrev_b64 v[44:45], 11, v[40:41]
	v_lshl_add_u64 v[108:109], s[4:5], 0, v[108:109]
	v_lshl_add_u64 v[44:45], s[4:5], 0, v[44:45]
	v_lshl_add_u64 v[108:109], v[108:109], 0, s[14:15]
	v_cvt_pk_bf16_f32 v93, v94, v95
	v_cvt_pk_bf16_f32 v94, v88, v89
	v_add_u32_e32 v88, s36, v140
	v_lshl_add_u64 v[44:45], v[44:45], 0, s[14:15]
	v_cvt_pk_bf16_f32 v28, v28, v29
	v_cvt_pk_bf16_f32 v29, v30, v31
	v_cvt_pk_bf16_f32 v30, v24, v25
	v_add_u32_e32 v24, s36, v144
	v_lshl_add_u64 v[108:109], v[108:109], 0, v[132:133]
	v_cvt_pk_bf16_f32 v95, v90, v91
	v_ashrrev_i32_e32 v89, 31, v88
	v_lshl_add_u64 v[44:45], v[44:45], 0, v[132:133]
	v_cvt_pk_bf16_f32 v31, v26, v27
	v_ashrrev_i32_e32 v25, 31, v24
	global_store_dwordx4 v[108:109], v[92:95], off offset:256
	global_store_dwordx4 v[44:45], v[28:31], off offset:256
	v_cvt_pk_bf16_f32 v76, v76, v77
	v_lshlrev_b64 v[92:93], 11, v[88:89]
	v_lshlrev_b64 v[28:29], 11, v[24:25]
	v_lshl_add_u64 v[92:93], s[4:5], 0, v[92:93]
	v_lshl_add_u64 v[28:29], s[4:5], 0, v[28:29]
	v_lshl_add_u64 v[92:93], v[92:93], 0, s[14:15]
	v_cvt_pk_bf16_f32 v77, v78, v79
	v_cvt_pk_bf16_f32 v78, v72, v73
	v_add_u32_e32 v72, s36, v141
	v_lshl_add_u64 v[28:29], v[28:29], 0, s[14:15]
	v_cvt_pk_bf16_f32 v12, v12, v13
	v_cvt_pk_bf16_f32 v13, v14, v15
	v_cvt_pk_bf16_f32 v14, v8, v9
	v_add_u32_e32 v8, s36, v145
	v_lshl_add_u64 v[92:93], v[92:93], 0, v[132:133]
	v_cvt_pk_bf16_f32 v79, v74, v75
	v_ashrrev_i32_e32 v73, 31, v72
	v_lshl_add_u64 v[28:29], v[28:29], 0, v[132:133]
	v_cvt_pk_bf16_f32 v15, v10, v11
	v_ashrrev_i32_e32 v9, 31, v8
	global_store_dwordx4 v[92:93], v[76:79], off offset:256
	global_store_dwordx4 v[28:29], v[12:15], off offset:256
	v_cvt_pk_bf16_f32 v127, v122, v123
	v_lshlrev_b64 v[76:77], 11, v[72:73]
	v_lshlrev_b64 v[12:13], 11, v[8:9]
	v_lshl_add_u64 v[76:77], s[4:5], 0, v[76:77]
	v_lshl_add_u64 v[12:13], s[4:5], 0, v[12:13]
	v_lshl_add_u64 v[76:77], v[76:77], 0, s[14:15]
	v_lshl_add_u64 v[12:13], v[12:13], 0, s[14:15]
	v_cvt_pk_bf16_f32 v104, v116, v117
	v_cvt_pk_bf16_f32 v105, v118, v119
	v_cvt_pk_bf16_f32 v106, v112, v113
	v_cvt_pk_bf16_f32 v107, v114, v115
	v_cvt_pk_bf16_f32 v88, v100, v101
	v_cvt_pk_bf16_f32 v89, v102, v103
	v_cvt_pk_bf16_f32 v90, v96, v97
	v_cvt_pk_bf16_f32 v91, v98, v99
	v_cvt_pk_bf16_f32 v72, v84, v85
	v_cvt_pk_bf16_f32 v73, v86, v87
	v_cvt_pk_bf16_f32 v74, v80, v81
	v_cvt_pk_bf16_f32 v75, v82, v83
	v_lshl_add_u64 v[76:77], v[76:77], 0, v[132:133]
	v_cvt_pk_bf16_f32 v71, v66, v67
	v_cvt_pk_bf16_f32 v63, v58, v59
	v_cvt_pk_bf16_f32 v40, v52, v53
	v_cvt_pk_bf16_f32 v41, v54, v55
	v_cvt_pk_bf16_f32 v42, v48, v49
	v_cvt_pk_bf16_f32 v43, v50, v51
	v_cvt_pk_bf16_f32 v24, v36, v37
	v_cvt_pk_bf16_f32 v25, v38, v39
	v_cvt_pk_bf16_f32 v26, v32, v33
	v_cvt_pk_bf16_f32 v27, v34, v35
	v_cvt_pk_bf16_f32 v8, v20, v21
	v_cvt_pk_bf16_f32 v9, v22, v23
	v_cvt_pk_bf16_f32 v10, v16, v17
	v_cvt_pk_bf16_f32 v11, v18, v19
	v_lshl_add_u64 v[12:13], v[12:13], 0, v[132:133]
	v_cvt_pk_bf16_f32 v4, v4, v5
	v_cvt_pk_bf16_f32 v5, v6, v7
	v_cvt_pk_bf16_f32 v6, v0, v1
	v_cvt_pk_bf16_f32 v7, v2, v3
	s_andn2_b64 vcc, exec, s[6:7]
	s_mov_b64 s[6:7], -1
	global_store_dwordx4 v[120:121], v[124:127], off
	global_store_dwordx4 v[108:109], v[104:107], off
	global_store_dwordx4 v[92:93], v[88:91], off
	global_store_dwordx4 v[76:77], v[72:75], off
	global_store_dwordx4 v[76:77], v[68:71], off offset:256
	global_store_dwordx4 v[56:57], v[60:63], off
	global_store_dwordx4 v[44:45], v[40:43], off
	global_store_dwordx4 v[28:29], v[24:27], off
	global_store_dwordx4 v[12:13], v[8:11], off
	global_store_dwordx4 v[12:13], v[4:7], off offset:256
	s_cbranch_vccnz .LBB0_925
	s_andn2_b64 vcc, exec, s[10:11]
	s_cbranch_vccnz .LBB0_924
	s_barrier
	s_branch .LBB0_924

; DI float sigmoidf_(float x) { return __builtin_amdgcn_rcpf(1.0f + __builtin_amdgcn_exp2f(-1.4426950408889634f * x)); }
; #define EPI_ROWS(...) _Pragma("unroll") for (int ai = 0; ai < 2; ++ai) _Pragma("unroll") for (int m = 0; m < 4; ++m) { const int rr = ai * 128 + wr * 64 + m * 16 + fr; __VA_ARGS__ }
;     DI void operator()(const Acc& acc, int wr, int wc, int fr, int fq) const {
;         EPI_ROWS(const size_t row = row0 + rr; const int cc = wc * 32 + 8 * fq; u32x4 w;
;             { const f32x4 a = acc[ai][0][m][0], u = acc[ai][1][m][0]; w.x = pk2(a[0] * sigmoidf_(a[0]) * u[0], a[1] * sigmoidf_(a[1]) * u[1]); w.y = pk2(a[2] * sigmoidf_(a[2]) * u[2], a[3] * sigmoidf_(a[3]) * u[3]); }
;             { const f32x4 a = acc[ai][0][m][1], u = acc[ai][1][m][1]; w.z = pk2(a[0] * sigmoidf_(a[0]) * u[0], a[1] * sigmoidf_(a[1]) * u[1]); w.w = pk2(a[2] * sigmoidf_(a[2]) * u[2], a[3] * sigmoidf_(a[3]) * u[3]); }
;             *(u32x4*)(hact + row * FF + hb * 128 + cc) = w;)
;     }
.LBB0_1057:
	v_mul_f32_e32 v149, 0xbfb8aa3b, v124
	v_exp_f32_e32 v149, v149
	v_mul_f32_e32 v150, 0xbfb8aa3b, v125
	v_exp_f32_e32 v151, v150
	v_add_u32_e32 v154, s42, v137
	v_add_f32_e32 v149, 1.0, v149
	v_rcp_f32_e32 v150, v149
	v_add_f32_e32 v149, 1.0, v151
	v_mul_f32_e32 v151, 0xbfb8aa3b, v126
	v_exp_f32_e32 v152, v151
	v_mul_f32_e32 v151, 0xbfb8aa3b, v127
	v_exp_f32_e32 v153, v151
	v_rcp_f32_e32 v151, v149
	v_add_f32_e32 v149, 1.0, v152
	v_rcp_f32_e32 v152, v149
	v_add_f32_e32 v149, 1.0, v153
	v_rcp_f32_e32 v153, v149
	v_pk_mul_f32 v[124:125], v[124:125], v[150:151]
	s_andn2_b64 vcc, exec, s[6:7]
	v_pk_mul_f32 v[120:121], v[124:125], v[120:121]
	v_pk_mul_f32 v[124:125], v[126:127], v[152:153]
	v_cvt_pk_bf16_f32 v120, v120, v121
	v_mul_f32_e32 v121, 0xbfb8aa3b, v116
	v_pk_mul_f32 v[122:123], v[124:125], v[122:123]
	v_exp_f32_e32 v124, v121
	v_mul_f32_e32 v121, 0xbfb8aa3b, v117
	v_exp_f32_e32 v125, v121
	v_cvt_pk_bf16_f32 v121, v122, v123
	v_add_f32_e32 v122, 1.0, v124
	v_mul_f32_e32 v124, 0xbfb8aa3b, v118
	v_add_f32_e32 v123, 1.0, v125
	v_mul_f32_e32 v125, 0xbfb8aa3b, v119
	v_exp_f32_e32 v124, v124
	v_exp_f32_e32 v125, v125
	v_rcp_f32_e32 v122, v122
	v_rcp_f32_e32 v123, v123
	v_add_f32_e32 v124, 1.0, v124
	v_add_f32_e32 v125, 1.0, v125
	v_rcp_f32_e32 v124, v124
	v_rcp_f32_e32 v125, v125
	v_pk_mul_f32 v[116:117], v[116:117], v[122:123]
	s_mov_b64 s[6:7], -1
	v_pk_mul_f32 v[112:113], v[116:117], v[112:113]
	v_mul_f32_e32 v116, 0xbfb8aa3b, v110
	v_cvt_pk_bf16_f32 v122, v112, v113
	v_pk_mul_f32 v[112:113], v[118:119], v[124:125]
	v_mul_f32_e32 v117, 0xbfb8aa3b, v111
	v_pk_mul_f32 v[112:113], v[112:113], v[114:115]
	v_exp_f32_e32 v116, v116
	v_cvt_pk_bf16_f32 v123, v112, v113
	v_mov_b64_e32 v[112:113], s[8:9]
	v_mad_i64_i32 v[114:115], s[20:21], v154, s41, v[112:113]
	s_lshl_b32 s20, s43, 7
	s_ashr_i32 s21, s20, 31
	s_lshl_b64 s[20:21], s[20:21], 1
	v_lshl_add_u64 v[114:115], v[114:115], 0, s[20:21]
	v_lshl_add_u64 v[114:115], v[114:115], 0, v[132:133]
	global_store_dwordx4 v[114:115], v[120:123], off
	v_mul_f32_e32 v114, 0xbfb8aa3b, v108
	v_mul_f32_e32 v115, 0xbfb8aa3b, v109
	v_exp_f32_e32 v114, v114
	v_exp_f32_e32 v115, v115
	v_exp_f32_e32 v117, v117
	v_add_f32_e32 v116, 1.0, v116
	v_add_f32_e32 v114, 1.0, v114
	v_add_f32_e32 v115, 1.0, v115
	v_rcp_f32_e32 v114, v114
	v_rcp_f32_e32 v115, v115
	v_add_f32_e32 v117, 1.0, v117
	v_rcp_f32_e32 v116, v116
	v_rcp_f32_e32 v117, v117
	v_pk_mul_f32 v[108:109], v[108:109], v[114:115]
	v_add_u32_e32 v118, s42, v139
	v_pk_mul_f32 v[104:105], v[108:109], v[104:105]
	v_pk_mul_f32 v[108:109], v[110:111], v[116:117]
	v_cvt_pk_bf16_f32 v104, v104, v105
	v_mul_f32_e32 v105, 0xbfb8aa3b, v100
	v_pk_mul_f32 v[106:107], v[108:109], v[106:107]
	v_exp_f32_e32 v108, v105
	v_mul_f32_e32 v105, 0xbfb8aa3b, v101
	v_exp_f32_e32 v109, v105
	v_cvt_pk_bf16_f32 v105, v106, v107
	v_add_f32_e32 v106, 1.0, v108
	v_mul_f32_e32 v108, 0xbfb8aa3b, v102
	v_add_f32_e32 v107, 1.0, v109
	v_mul_f32_e32 v109, 0xbfb8aa3b, v103
	v_exp_f32_e32 v108, v108
	v_exp_f32_e32 v109, v109
	v_rcp_f32_e32 v106, v106
	v_rcp_f32_e32 v107, v107
	v_add_f32_e32 v108, 1.0, v108
	v_add_f32_e32 v109, 1.0, v109
	v_rcp_f32_e32 v108, v108
	v_rcp_f32_e32 v109, v109
	v_pk_mul_f32 v[100:101], v[100:101], v[106:107]
	s_nop 0
	v_pk_mul_f32 v[96:97], v[100:101], v[96:97]
	v_add_u32_e32 v100, s42, v140
	v_cvt_pk_bf16_f32 v106, v96, v97
	v_pk_mul_f32 v[96:97], v[102:103], v[108:109]
	s_nop 0
	v_pk_mul_f32 v[96:97], v[96:97], v[98:99]
	v_mul_f32_e32 v98, 0xbfb8aa3b, v94
	v_cvt_pk_bf16_f32 v107, v96, v97
	v_mad_i64_i32 v[96:97], s[22:23], v118, s41, v[112:113]
	v_lshl_add_u64 v[96:97], v[96:97], 0, s[20:21]
	v_lshl_add_u64 v[96:97], v[96:97], 0, v[132:133]
	global_store_dwordx4 v[96:97], v[104:107], off
	v_mul_f32_e32 v96, 0xbfb8aa3b, v92
	v_mul_f32_e32 v97, 0xbfb8aa3b, v93
	v_exp_f32_e32 v96, v96
	v_exp_f32_e32 v97, v97
	v_mul_f32_e32 v99, 0xbfb8aa3b, v95
	v_exp_f32_e32 v98, v98
	v_exp_f32_e32 v99, v99
	v_add_f32_e32 v96, 1.0, v96
	v_add_f32_e32 v97, 1.0, v97
	v_rcp_f32_e32 v96, v96
	v_rcp_f32_e32 v97, v97
	v_add_f32_e32 v98, 1.0, v98
	v_add_f32_e32 v99, 1.0, v99
	v_rcp_f32_e32 v98, v98
	v_rcp_f32_e32 v99, v99
	v_pk_mul_f32 v[92:93], v[92:93], v[96:97]
	s_nop 0
	v_pk_mul_f32 v[88:89], v[92:93], v[88:89]
	v_pk_mul_f32 v[92:93], v[94:95], v[98:99]
	v_cvt_pk_bf16_f32 v88, v88, v89
	v_mul_f32_e32 v89, 0xbfb8aa3b, v84
	v_pk_mul_f32 v[90:91], v[92:93], v[90:91]
	v_exp_f32_e32 v92, v89
	v_mul_f32_e32 v89, 0xbfb8aa3b, v85
	v_exp_f32_e32 v93, v89
	v_cvt_pk_bf16_f32 v89, v90, v91
	v_add_f32_e32 v90, 1.0, v92
	v_mul_f32_e32 v92, 0xbfb8aa3b, v86
	v_add_f32_e32 v91, 1.0, v93
	v_mul_f32_e32 v93, 0xbfb8aa3b, v87
	v_exp_f32_e32 v92, v92
	v_exp_f32_e32 v93, v93
	v_rcp_f32_e32 v90, v90
	v_rcp_f32_e32 v91, v91
	v_add_f32_e32 v92, 1.0, v92
	v_add_f32_e32 v93, 1.0, v93
	v_rcp_f32_e32 v92, v92
	v_rcp_f32_e32 v93, v93
	v_pk_mul_f32 v[84:85], v[84:85], v[90:91]
	s_nop 0
	v_pk_mul_f32 v[80:81], v[84:85], v[80:81]
	v_add_u32_e32 v84, s42, v141
	v_cvt_pk_bf16_f32 v90, v80, v81
	v_pk_mul_f32 v[80:81], v[86:87], v[92:93]
	s_nop 0
	v_pk_mul_f32 v[80:81], v[80:81], v[82:83]
	v_mul_f32_e32 v82, 0xbfb8aa3b, v78
	v_cvt_pk_bf16_f32 v91, v80, v81
	v_mad_i64_i32 v[80:81], s[22:23], v100, s41, v[112:113]
	v_lshl_add_u64 v[80:81], v[80:81], 0, s[20:21]
	v_lshl_add_u64 v[80:81], v[80:81], 0, v[132:133]
	global_store_dwordx4 v[80:81], v[88:91], off
	v_mul_f32_e32 v80, 0xbfb8aa3b, v76
	v_mul_f32_e32 v81, 0xbfb8aa3b, v77
	v_exp_f32_e32 v80, v80
	v_exp_f32_e32 v81, v81
	v_mul_f32_e32 v83, 0xbfb8aa3b, v79
	v_exp_f32_e32 v82, v82
	v_exp_f32_e32 v83, v83
	v_add_f32_e32 v80, 1.0, v80
	v_add_f32_e32 v81, 1.0, v81
; DI float sigmoidf_(float x) { return __builtin_amdgcn_rcpf(1.0f + __builtin_amdgcn_exp2f(-1.4426950408889634f * x)); }
; #define EPI_ROWS(...) _Pragma("unroll") for (int ai = 0; ai < 2; ++ai) _Pragma("unroll") for (int m = 0; m < 4; ++m) { const int rr = ai * 128 + wr * 64 + m * 16 + fr; __VA_ARGS__ }
;     DI void operator()(const Acc& acc, int wr, int wc, int fr, int fq) const {
;         EPI_ROWS(const size_t row = row0 + rr; const int cc = wc * 32 + 8 * fq; u32x4 w;
;             { const f32x4 a = acc[ai][0][m][0], u = acc[ai][1][m][0]; w.x = pk2(a[0] * sigmoidf_(a[0]) * u[0], a[1] * sigmoidf_(a[1]) * u[1]); w.y = pk2(a[2] * sigmoidf_(a[2]) * u[2], a[3] * sigmoidf_(a[3]) * u[3]); }
;             { const f32x4 a = acc[ai][0][m][1], u = acc[ai][1][m][1]; w.z = pk2(a[0] * sigmoidf_(a[0]) * u[0], a[1] * sigmoidf_(a[1]) * u[1]); w.w = pk2(a[2] * sigmoidf_(a[2]) * u[2], a[3] * sigmoidf_(a[3]) * u[3]); }
;             *(u32x4*)(hact + row * FF + hb * 128 + cc) = w;)
;     }
	v_rcp_f32_e32 v80, v80
	v_rcp_f32_e32 v81, v81
	v_add_f32_e32 v82, 1.0, v82
	v_add_f32_e32 v83, 1.0, v83
	v_rcp_f32_e32 v82, v82
	v_rcp_f32_e32 v83, v83
	v_pk_mul_f32 v[76:77], v[76:77], v[80:81]
	s_nop 0
	v_pk_mul_f32 v[72:73], v[76:77], v[72:73]
	v_pk_mul_f32 v[76:77], v[78:79], v[82:83]
	v_cvt_pk_bf16_f32 v72, v72, v73
	v_mul_f32_e32 v73, 0xbfb8aa3b, v68
	v_pk_mul_f32 v[74:75], v[76:77], v[74:75]
	v_exp_f32_e32 v76, v73
	v_mul_f32_e32 v73, 0xbfb8aa3b, v69
	v_exp_f32_e32 v77, v73
	v_cvt_pk_bf16_f32 v73, v74, v75
	v_add_f32_e32 v74, 1.0, v76
	v_mul_f32_e32 v76, 0xbfb8aa3b, v70
	v_add_f32_e32 v75, 1.0, v77
	v_mul_f32_e32 v77, 0xbfb8aa3b, v71
	v_exp_f32_e32 v76, v76
	v_exp_f32_e32 v77, v77
	v_rcp_f32_e32 v74, v74
	v_rcp_f32_e32 v75, v75
	v_add_f32_e32 v76, 1.0, v76
	v_add_f32_e32 v77, 1.0, v77
	v_rcp_f32_e32 v76, v76
	v_rcp_f32_e32 v77, v77
	v_pk_mul_f32 v[68:69], v[68:69], v[74:75]
	s_nop 0
	v_pk_mul_f32 v[64:65], v[68:69], v[64:65]
	v_add_u32_e32 v68, s42, v142
	v_cvt_pk_bf16_f32 v74, v64, v65
	v_pk_mul_f32 v[64:65], v[70:71], v[76:77]
	s_nop 0
	v_pk_mul_f32 v[64:65], v[64:65], v[66:67]
	v_mul_f32_e32 v66, 0xbfb8aa3b, v62
	v_cvt_pk_bf16_f32 v75, v64, v65
	v_mad_i64_i32 v[64:65], s[22:23], v84, s41, v[112:113]
	v_lshl_add_u64 v[64:65], v[64:65], 0, s[20:21]
	v_lshl_add_u64 v[64:65], v[64:65], 0, v[132:133]
	global_store_dwordx4 v[64:65], v[72:75], off
	v_mul_f32_e32 v64, 0xbfb8aa3b, v60
	v_mul_f32_e32 v65, 0xbfb8aa3b, v61
	v_exp_f32_e32 v64, v64
	v_exp_f32_e32 v65, v65
	v_mul_f32_e32 v67, 0xbfb8aa3b, v63
	v_exp_f32_e32 v66, v66
	v_exp_f32_e32 v67, v67
	v_add_f32_e32 v64, 1.0, v64
	v_add_f32_e32 v65, 1.0, v65
	v_rcp_f32_e32 v64, v64
	v_rcp_f32_e32 v65, v65
	v_add_f32_e32 v66, 1.0, v66
	v_add_f32_e32 v67, 1.0, v67
	v_rcp_f32_e32 v66, v66
	v_rcp_f32_e32 v67, v67
	v_pk_mul_f32 v[60:61], v[60:61], v[64:65]
	s_nop 0
	v_pk_mul_f32 v[56:57], v[60:61], v[56:57]
	v_pk_mul_f32 v[60:61], v[62:63], v[66:67]
	v_cvt_pk_bf16_f32 v56, v56, v57
	v_mul_f32_e32 v57, 0xbfb8aa3b, v52
	v_pk_mul_f32 v[58:59], v[60:61], v[58:59]
	v_exp_f32_e32 v60, v57
	v_mul_f32_e32 v57, 0xbfb8aa3b, v53
	v_exp_f32_e32 v61, v57
	v_cvt_pk_bf16_f32 v57, v58, v59
	v_add_f32_e32 v58, 1.0, v60
	v_mul_f32_e32 v60, 0xbfb8aa3b, v54
	v_add_f32_e32 v59, 1.0, v61
	v_mul_f32_e32 v61, 0xbfb8aa3b, v55
	v_exp_f32_e32 v60, v60
	v_exp_f32_e32 v61, v61
	v_rcp_f32_e32 v58, v58
	v_rcp_f32_e32 v59, v59
	v_add_f32_e32 v60, 1.0, v60
	v_add_f32_e32 v61, 1.0, v61
	v_rcp_f32_e32 v60, v60
	v_rcp_f32_e32 v61, v61
	v_pk_mul_f32 v[52:53], v[52:53], v[58:59]
	s_nop 0
	v_pk_mul_f32 v[48:49], v[52:53], v[48:49]
	v_add_u32_e32 v52, s42, v143
	v_cvt_pk_bf16_f32 v58, v48, v49
	v_pk_mul_f32 v[48:49], v[54:55], v[60:61]
	s_nop 0
	v_pk_mul_f32 v[48:49], v[48:49], v[50:51]
	v_mul_f32_e32 v50, 0xbfb8aa3b, v46
	v_cvt_pk_bf16_f32 v59, v48, v49
	v_mad_i64_i32 v[48:49], s[22:23], v68, s41, v[112:113]
	v_lshl_add_u64 v[48:49], v[48:49], 0, s[20:21]
	v_lshl_add_u64 v[48:49], v[48:49], 0, v[132:133]
	global_store_dwordx4 v[48:49], v[56:59], off
	v_mul_f32_e32 v48, 0xbfb8aa3b, v44
	v_mul_f32_e32 v49, 0xbfb8aa3b, v45
	v_exp_f32_e32 v48, v48
	v_exp_f32_e32 v49, v49
	v_mul_f32_e32 v51, 0xbfb8aa3b, v47
	v_exp_f32_e32 v50, v50
	v_exp_f32_e32 v51, v51
	v_add_f32_e32 v48, 1.0, v48
	v_add_f32_e32 v49, 1.0, v49
	v_rcp_f32_e32 v48, v48
	v_rcp_f32_e32 v49, v49
	v_add_f32_e32 v50, 1.0, v50
	v_add_f32_e32 v51, 1.0, v51
	v_rcp_f32_e32 v50, v50
	v_rcp_f32_e32 v51, v51
	v_pk_mul_f32 v[44:45], v[44:45], v[48:49]
	s_nop 0
	v_pk_mul_f32 v[40:41], v[44:45], v[40:41]
	v_pk_mul_f32 v[44:45], v[46:47], v[50:51]
	v_cvt_pk_bf16_f32 v40, v40, v41
	v_mul_f32_e32 v41, 0xbfb8aa3b, v36
	v_pk_mul_f32 v[42:43], v[44:45], v[42:43]
	v_exp_f32_e32 v44, v41
	v_mul_f32_e32 v41, 0xbfb8aa3b, v37
	v_exp_f32_e32 v45, v41
	v_cvt_pk_bf16_f32 v41, v42, v43
	v_add_f32_e32 v42, 1.0, v44
	v_mul_f32_e32 v44, 0xbfb8aa3b, v38
	v_add_f32_e32 v43, 1.0, v45
	v_mul_f32_e32 v45, 0xbfb8aa3b, v39
	v_exp_f32_e32 v44, v44
	v_exp_f32_e32 v45, v45
; DI float sigmoidf_(float x) { return __builtin_amdgcn_rcpf(1.0f + __builtin_amdgcn_exp2f(-1.4426950408889634f * x)); }
; #define BAR __builtin_amdgcn_s_barrier()
; #define ZERO_ACC() do { _Pragma("unroll") for (int a = 0; a < 2; ++a) _Pragma("unroll") for (int b = 0; b < 2; ++b) _Pragma("unroll") for (int m = 0; m < 4; ++m) _Pragma("unroll") for (int n = 0; n < 2; ++n) acc[a][b][m][n] = (f32x4){0.f, 0.f, 0.f, 0.f}; } while (0)
; #define EPI_ROWS(...) _Pragma("unroll") for (int ai = 0; ai < 2; ++ai) _Pragma("unroll") for (int m = 0; m < 4; ++m) { const int rr = ai * 128 + wr * 64 + m * 16 + fr; __VA_ARGS__ }
; template <class Units>
; DI void gemm_phase(LAS unsigned char* lds, const int wid, const int lda, const int ldb, const int K, const Units& U) {
;     ...
;         if (wr == 0) BAR;
;         Ecur(acc, wr, wc, fr, fq);
;         if (!has_next) break;
;         ZERO_ACC();
;         cA = nA; cB = nB; Ecur = Enxt;
;         if (wr == 1) BAR;
;     DI void operator()(const Acc& acc, int wr, int wc, int fr, int fq) const {
;         EPI_ROWS(const size_t row = row0 + rr; const int cc = wc * 32 + 8 * fq; u32x4 w;
;             { const f32x4 a = acc[ai][0][m][0], u = acc[ai][1][m][0]; w.x = pk2(a[0] * sigmoidf_(a[0]) * u[0], a[1] * sigmoidf_(a[1]) * u[1]); w.y = pk2(a[2] * sigmoidf_(a[2]) * u[2], a[3] * sigmoidf_(a[3]) * u[3]); }
;             { const f32x4 a = acc[ai][0][m][1], u = acc[ai][1][m][1]; w.z = pk2(a[0] * sigmoidf_(a[0]) * u[0], a[1] * sigmoidf_(a[1]) * u[1]); w.w = pk2(a[2] * sigmoidf_(a[2]) * u[2], a[3] * sigmoidf_(a[3]) * u[3]); }
;             *(u32x4*)(hact + row * FF + hb * 128 + cc) = w;)
;     }
	v_rcp_f32_e32 v42, v42
	v_rcp_f32_e32 v43, v43
	v_add_f32_e32 v44, 1.0, v44
	v_add_f32_e32 v45, 1.0, v45
	v_rcp_f32_e32 v44, v44
	v_rcp_f32_e32 v45, v45
	v_pk_mul_f32 v[36:37], v[36:37], v[42:43]
	s_nop 0
	v_pk_mul_f32 v[32:33], v[36:37], v[32:33]
	v_add_u32_e32 v36, s42, v144
	v_cvt_pk_bf16_f32 v42, v32, v33
	v_pk_mul_f32 v[32:33], v[38:39], v[44:45]
	s_nop 0
	v_pk_mul_f32 v[32:33], v[32:33], v[34:35]
	v_mul_f32_e32 v34, 0xbfb8aa3b, v30
	v_cvt_pk_bf16_f32 v43, v32, v33
	v_mad_i64_i32 v[32:33], s[22:23], v52, s41, v[112:113]
	v_lshl_add_u64 v[32:33], v[32:33], 0, s[20:21]
	v_lshl_add_u64 v[32:33], v[32:33], 0, v[132:133]
	global_store_dwordx4 v[32:33], v[40:43], off
	v_mul_f32_e32 v32, 0xbfb8aa3b, v28
	v_mul_f32_e32 v33, 0xbfb8aa3b, v29
	v_exp_f32_e32 v32, v32
	v_exp_f32_e32 v33, v33
	v_mul_f32_e32 v35, 0xbfb8aa3b, v31
	v_exp_f32_e32 v34, v34
	v_exp_f32_e32 v35, v35
	v_add_f32_e32 v32, 1.0, v32
	v_add_f32_e32 v33, 1.0, v33
	v_rcp_f32_e32 v32, v32
	v_rcp_f32_e32 v33, v33
	v_add_f32_e32 v34, 1.0, v34
	v_add_f32_e32 v35, 1.0, v35
	v_rcp_f32_e32 v34, v34
	v_rcp_f32_e32 v35, v35
	v_pk_mul_f32 v[28:29], v[28:29], v[32:33]
	s_nop 0
	v_pk_mul_f32 v[24:25], v[28:29], v[24:25]
	v_pk_mul_f32 v[28:29], v[30:31], v[34:35]
	v_cvt_pk_bf16_f32 v24, v24, v25
	v_mul_f32_e32 v25, 0xbfb8aa3b, v20
	v_pk_mul_f32 v[26:27], v[28:29], v[26:27]
	v_exp_f32_e32 v28, v25
	v_mul_f32_e32 v25, 0xbfb8aa3b, v21
	v_exp_f32_e32 v29, v25
	v_cvt_pk_bf16_f32 v25, v26, v27
	v_add_f32_e32 v26, 1.0, v28
	v_mul_f32_e32 v28, 0xbfb8aa3b, v22
	v_add_f32_e32 v27, 1.0, v29
	v_mul_f32_e32 v29, 0xbfb8aa3b, v23
	v_exp_f32_e32 v28, v28
	v_exp_f32_e32 v29, v29
	v_rcp_f32_e32 v26, v26
	v_rcp_f32_e32 v27, v27
	v_add_f32_e32 v28, 1.0, v28
	v_add_f32_e32 v29, 1.0, v29
	v_rcp_f32_e32 v28, v28
	v_rcp_f32_e32 v29, v29
	v_pk_mul_f32 v[20:21], v[20:21], v[26:27]
	s_nop 0
	v_pk_mul_f32 v[16:17], v[20:21], v[16:17]
	v_add_u32_e32 v20, s42, v145
	v_cvt_pk_bf16_f32 v26, v16, v17
	v_pk_mul_f32 v[16:17], v[22:23], v[28:29]
	s_nop 0
	v_pk_mul_f32 v[16:17], v[16:17], v[18:19]
	v_mul_f32_e32 v18, 0xbfb8aa3b, v14
	v_cvt_pk_bf16_f32 v27, v16, v17
	v_mad_i64_i32 v[16:17], s[22:23], v36, s41, v[112:113]
	v_lshl_add_u64 v[16:17], v[16:17], 0, s[20:21]
	v_lshl_add_u64 v[16:17], v[16:17], 0, v[132:133]
	global_store_dwordx4 v[16:17], v[24:27], off
	v_mul_f32_e32 v16, 0xbfb8aa3b, v12
	v_mul_f32_e32 v17, 0xbfb8aa3b, v13
	v_exp_f32_e32 v16, v16
	v_exp_f32_e32 v17, v17
	v_mul_f32_e32 v19, 0xbfb8aa3b, v15
	v_exp_f32_e32 v18, v18
	v_exp_f32_e32 v19, v19
	v_add_f32_e32 v16, 1.0, v16
	v_add_f32_e32 v17, 1.0, v17
	v_rcp_f32_e32 v16, v16
	v_rcp_f32_e32 v17, v17
	v_add_f32_e32 v18, 1.0, v18
	v_add_f32_e32 v19, 1.0, v19
	v_rcp_f32_e32 v18, v18
	v_rcp_f32_e32 v19, v19
	v_pk_mul_f32 v[12:13], v[12:13], v[16:17]
	s_nop 0
	v_pk_mul_f32 v[8:9], v[12:13], v[8:9]
	v_pk_mul_f32 v[12:13], v[14:15], v[18:19]
	v_cvt_pk_bf16_f32 v8, v8, v9
	v_mul_f32_e32 v9, 0xbfb8aa3b, v4
	v_pk_mul_f32 v[10:11], v[12:13], v[10:11]
	v_exp_f32_e32 v12, v9
	v_mul_f32_e32 v9, 0xbfb8aa3b, v5
	v_exp_f32_e32 v13, v9
	v_cvt_pk_bf16_f32 v9, v10, v11
	v_add_f32_e32 v10, 1.0, v12
	v_mul_f32_e32 v12, 0xbfb8aa3b, v6
	v_add_f32_e32 v11, 1.0, v13
	v_mul_f32_e32 v13, 0xbfb8aa3b, v7
	v_exp_f32_e32 v12, v12
	v_exp_f32_e32 v13, v13
	v_rcp_f32_e32 v10, v10
	v_rcp_f32_e32 v11, v11
	v_add_f32_e32 v12, 1.0, v12
	v_add_f32_e32 v13, 1.0, v13
	v_rcp_f32_e32 v12, v12
	v_rcp_f32_e32 v13, v13
	v_pk_mul_f32 v[4:5], v[4:5], v[10:11]
	s_nop 0
	v_pk_mul_f32 v[0:1], v[4:5], v[0:1]
	s_nop 0
	v_cvt_pk_bf16_f32 v10, v0, v1
	v_pk_mul_f32 v[0:1], v[6:7], v[12:13]
	s_nop 0
	v_pk_mul_f32 v[0:1], v[0:1], v[2:3]
	s_nop 0
	v_cvt_pk_bf16_f32 v11, v0, v1
	v_mad_i64_i32 v[0:1], s[22:23], v20, s41, v[112:113]
	v_lshl_add_u64 v[0:1], v[0:1], 0, s[20:21]
	v_lshl_add_u64 v[0:1], v[0:1], 0, v[132:133]
	global_store_dwordx4 v[0:1], v[8:11], off
	s_cbranch_vccnz .LBB0_1050
	s_andn2_b64 vcc, exec, s[12:13]
	s_cbranch_vccnz .LBB0_1049
	s_barrier
	s_branch .LBB0_1049
